# baseline (speedup 1.0000x reference)
; template <int MODE> ...
;     ...
;                 float sacc = 0.f;
; #pragma unroll
;                 for (int r = 0; r < 16; ++r) { p0[r] = ex2(p0[r] - mhat); p1[r] = ex2(p1[r] - mhat); sacc += p0[r] + p1[r]; }
;                 lsum += sacc;
;             } else {
;                 f32x16 L0, L1;
; #pragma unroll
;                 for (int r = 0; r < 16; ++r) {
;                     const float s0 = p0[r], s1 = p1[r];
;                     float l0 = lg2(1.0f + ex2(s0)), l1 = lg2(1.0f + ex2(s1));
;                     l0 = s0 > 32.f ? s0 : l0; l1 = s1 > 32.f ? s1 : l1;
;                     float g0 = s0 - l0, g1 = s1 - l1;
;                     if (!full) { const int k0 = crow(r, hi_m), k1 = k0 + 32; if (!(k0 < dq)) { l0 = 0.f; g0 = -INFINITY; } if (!(k1 < dq)) { l1 = 0.f; g1 = -INFINITY; } }
;                     L0[r] = l0; L1[r] = l1; p0[r] = g0; p1[r] = g1;
;                 }
;                 float T[8], U[8], Tp[8];
; #pragma unroll
;                 for (int g = 0; g < 8; ++g) { const int b = 4 * (g & 3);
;                     const float a0 = g < 4 ? L0[b] : L1[b], a1 = g < 4 ? L0[b + 1] : L1[b + 1], a2 = g < 4 ? L0[b + 2] : L1[b + 2], a3 = g < 4 ? L0[b + 3] : L1[b + 3];
;                     const float s2 = a3 + a2, s1 = s2 + a1; T[g] = s1 + a0;
;                     if (g < 4) { L0[b] = s1; L0[b + 1] = s2; L0[b + 2] = a3; L0[b + 3] = 0.f; } else { L1[b] = s1; L1[b + 1] = s2; L1[b + 2] = a3; L1[b + 3] = 0.f; }
;                     auto rr = __builtin_amdgcn_permlane32_swap(__float_as_uint(T[g]), __float_as_uint(T[g]), false, false);
;                     const float x0 = __uint_as_float(rr[0]), x1 = __uint_as_float(rr[1]);
;                     U[g] = x0 + x1; Tp[g] = hi == 0 ? x1 : 0.f; }
;                 float ss = 0.f;
; #pragma unroll
;                 for (int g = 7; g >= 0; --g) { const int b = 4 * (g & 3); const float base = Rp + ss + Tp[g];
; #pragma unroll
;                     for (int e = 0; e < 4; ++e) { if (g < 4) p0[b + e] = ex2(p0[b + e] - base - L0[b + e]); else p1[b + e] = ex2(p1[b + e] - base - L1[b + e]); }
;                     ss += U[g]; }
;                 Rp += ss;
;             }
;             pw0 = (u32x4){cvtpk(p0[0], p0[1]), cvtpk(p0[2], p0[3]), cvtpk(p0[4], p0[5]), cvtpk(p0[6], p0[7])};
;             pw1 = (u32x4){cvtpk(p0[8], p0[9]), cvtpk(p0[10], p0[11]), cvtpk(p0[12], p0[13]), cvtpk(p0[14], p0[15])};
.LBB0_241:
	s_andn2_b64 vcc, exec, s[6:7]
	s_cbranch_vccnz .Lmy_pv_skip
	s_mul_hi_u32 vcc_lo, s24, 0xaaaaaaab
	s_lshr_b32 vcc_lo, vcc_lo, 1
	s_mul_i32 vcc_lo, vcc_lo, 0xffff4000
	v_add_u32_e32 v189, vcc_lo, v182
	v_add3_u32 v189, v189, v147, s23
	ds_read_b64_tr_b16 v[190:191], v189
	ds_read_b64_tr_b16 v[192:193], v189 offset:512
	ds_read_b64_tr_b16 v[196:197], v189 offset:1024
	ds_read_b64_tr_b16 v[198:199], v189 offset:1536
	ds_read_b64_tr_b16 v[202:203], v189 offset:2048
	ds_read_b64_tr_b16 v[204:205], v189 offset:2560
	ds_read_b64_tr_b16 v[216:217], v189 offset:3072
	ds_read_b64_tr_b16 v[218:219], v189 offset:3584
	ds_read_b64_tr_b16 v[220:221], v189 offset:4096
	ds_read_b64_tr_b16 v[222:223], v189 offset:4608
	ds_read_b64_tr_b16 v[224:225], v189 offset:5120
	ds_read_b64_tr_b16 v[226:227], v189 offset:5632
	ds_read_b64_tr_b16 v[228:229], v189 offset:6144
	ds_read_b64_tr_b16 v[230:231], v189 offset:6656
	ds_read_b64_tr_b16 v[232:233], v189 offset:7168
	ds_read_b64_tr_b16 v[234:235], v189 offset:7680
	ds_read_b64_tr_b16 v[236:237], v189 offset:8192
	ds_read_b64_tr_b16 v[238:239], v189 offset:8704
	ds_read_b64_tr_b16 v[240:241], v189 offset:9216
	ds_read_b64_tr_b16 v[242:243], v189 offset:9728
	ds_read_b64_tr_b16 v[244:245], v189 offset:10240
	ds_read_b64_tr_b16 v[246:247], v189 offset:10752
	ds_read_b64_tr_b16 v[248:249], v189 offset:11264
	ds_read_b64_tr_b16 v[250:251], v189 offset:11776
	ds_read_b64_tr_b16 v[206:207], v189 offset:12288
	ds_read_b64_tr_b16 v[208:209], v189 offset:12800
	ds_read_b64_tr_b16 v[158:159], v189 offset:13312
	ds_read_b64_tr_b16 v[160:161], v189 offset:13824
	ds_read_b64_tr_b16 v[138:139], v189 offset:14336
	ds_read_b64_tr_b16 v[140:141], v189 offset:14848
	ds_read_b64_tr_b16 v[148:149], v189 offset:15360
	ds_read_b64_tr_b16 v[150:151], v189 offset:15872
.Lmy_pv_skip:
	v_sub_f32_e32 v0, v96, v184
	v_sub_f32_e32 v4, v83, v184
	v_exp_f32_e32 v3, v0
	v_sub_f32_e32 v0, v80, v184
	v_exp_f32_e32 v10, v4
	v_sub_f32_e32 v4, v100, v184
	v_sub_f32_e32 v8, v85, v184
	v_sub_f32_e32 v80, v89, v184
	v_exp_f32_e32 v9, v4
	v_sub_f32_e32 v4, v84, v184
	v_exp_f32_e32 v14, v8
	v_sub_f32_e32 v8, v102, v184
	v_exp_f32_e32 v102, v80
	v_sub_f32_e32 v80, v106, v184
	v_exp_f32_e32 v15, v4
	v_sub_f32_e32 v4, v101, v184
	v_exp_f32_e32 v101, v80
	v_sub_f32_e32 v80, v90, v184
	v_sub_f32_e32 v2, v81, v184
	v_sub_f32_e32 v12, v87, v184
	v_exp_f32_e32 v185, v80
	v_sub_f32_e32 v80, v107, v184
	v_exp_f32_e32 v6, v2
	v_sub_f32_e32 v2, v98, v184
	v_exp_f32_e32 v98, v12
	v_sub_f32_e32 v12, v104, v184
	v_exp_f32_e32 v96, v80
	v_sub_f32_e32 v80, v91, v184
	v_exp_f32_e32 v7, v0
	v_sub_f32_e32 v0, v97, v184
	v_exp_f32_e32 v5, v2
	v_sub_f32_e32 v2, v82, v184
	v_exp_f32_e32 v13, v8
	v_sub_f32_e32 v8, v86, v184
	v_exp_f32_e32 v97, v12
	v_sub_f32_e32 v12, v88, v184
	v_exp_f32_e32 v106, v80
	v_sub_f32_e32 v80, v108, v184
	v_exp_f32_e32 v11, v2
	v_sub_f32_e32 v2, v99, v184
	v_exp_f32_e32 v99, v8
	v_sub_f32_e32 v8, v103, v184
	v_exp_f32_e32 v103, v12
	v_sub_f32_e32 v12, v105, v184
	v_exp_f32_e32 v105, v80
	v_sub_f32_e32 v80, v92, v184
	v_exp_f32_e32 v187, v80
	v_sub_f32_e32 v80, v109, v184
	v_exp_f32_e32 v100, v80
	v_sub_f32_e32 v80, v93, v184
	v_exp_f32_e32 v108, v80
	v_sub_f32_e32 v80, v110, v184
	v_exp_f32_e32 v186, v80
	v_sub_f32_e32 v80, v94, v184
	v_exp_f32_e32 v188, v80
	v_sub_f32_e32 v80, v111, v184
	v_exp_f32_e32 v104, v80
	v_sub_f32_e32 v80, v95, v184
	v_exp_f32_e32 v0, v0
	v_exp_f32_e32 v2, v2
	v_exp_f32_e32 v4, v4
	v_exp_f32_e32 v8, v8
	v_exp_f32_e32 v12, v12
	v_exp_f32_e32 v110, v80
	s_mul_hi_u32 s14, s24, 0xaaaaaaab
	s_lshr_b32 s14, s14, 1
	v_cvt_pk_bf16_f32 v80, v3, v0
	v_cvt_pk_bf16_f32 v81, v5, v2
	v_cvt_pk_bf16_f32 v82, v9, v4
	v_cvt_pk_bf16_f32 v83, v13, v8
	v_cvt_pk_bf16_f32 v88, v97, v12
	v_cvt_pk_bf16_f32 v89, v101, v96
	v_cvt_pk_bf16_f32 v90, v105, v100
	v_cvt_pk_bf16_f32 v91, v186, v104
	v_cvt_pk_bf16_f32 v84, v7, v6
	v_cvt_pk_bf16_f32 v85, v11, v10
	v_cvt_pk_bf16_f32 v86, v15, v14
	v_cvt_pk_bf16_f32 v87, v99, v98
	v_cvt_pk_bf16_f32 v92, v103, v102
	v_cvt_pk_bf16_f32 v93, v185, v106
	v_cvt_pk_bf16_f32 v94, v187, v108
	s_andn2_b64 vcc, exec, s[6:7]
	v_cvt_pk_bf16_f32 v95, v188, v110
	s_cbranch_vccnz .LBB0_243
	s_waitcnt lgkmcnt(14)
	v_mfma_f32_32x32x16_bf16 v[64:79], v[80:83], v[190:193], v[64:79]
	v_mfma_f32_32x32x16_bf16 v[48:63], v[80:83], v[220:223], v[48:63]
	v_mfma_f32_32x32x16_bf16 v[64:79], v[88:91], v[196:199], v[64:79]
	v_mfma_f32_32x32x16_bf16 v[48:63], v[88:91], v[224:227], v[48:63]
	v_mfma_f32_32x32x16_bf16 v[64:79], v[84:87], v[202:205], v[64:79]
	v_mfma_f32_32x32x16_bf16 v[48:63], v[84:87], v[228:231], v[48:63]
	v_mfma_f32_32x32x16_bf16 v[64:79], v[92:95], v[216:219], v[64:79]
	v_mfma_f32_32x32x16_bf16 v[48:63], v[92:95], v[232:235], v[48:63]
	v_mfma_f32_32x32x16_bf16 v[32:47], v[80:83], v[236:239], v[32:47]
	s_waitcnt lgkmcnt(6)
	v_mfma_f32_32x32x16_bf16 v[16:31], v[80:83], v[206:209], v[16:31]
	v_mfma_f32_32x32x16_bf16 v[32:47], v[88:91], v[240:243], v[32:47]
	s_waitcnt lgkmcnt(4)
	v_mfma_f32_32x32x16_bf16 v[16:31], v[88:91], v[158:161], v[16:31]
	v_mfma_f32_32x32x16_bf16 v[32:47], v[84:87], v[244:247], v[32:47]
	s_waitcnt lgkmcnt(2)
	v_mfma_f32_32x32x16_bf16 v[16:31], v[84:87], v[138:141], v[16:31]
	v_mfma_f32_32x32x16_bf16 v[32:47], v[92:95], v[248:251], v[32:47]
	s_waitcnt lgkmcnt(0)
	v_mfma_f32_32x32x16_bf16 v[16:31], v[92:95], v[148:151], v[16:31]
	s_branch .LBB0_244
